# next-unit index math: group size is always 4, so the second runtime division (v_rcp + readfirstlane chain) becomes a shift and a mask
# speedup vs baseline: 1.0035x; 1.0004x over previous
;     __host__ __device__ bool next(int i, Unit& u) const {
;         const long L = (long)i * G + c; if (L >= nwg) return false;
;         int wgid = (int)L; { const int q = nwg / NXCD, r = nwg % NXCD, xcd = wgid % NXCD, off = wgid / NXCD; wgid = (xcd < r ? xcd * (q + 1) : r * (q + 1) + (xcd - r) * q) + off; }
;         const int nig = WGM * nN, gid = wgid / nig, fm = gid * WGM, gsz = (nM - fm) < WGM ? (nM - fm) : WGM;
;         u.pm = fm + ((wgid % nig) % gsz); u.pn = (wgid % nig) / gsz; return true;
;     }
.LBB0_293:
	s_add_i32 s93, s93, 1
	s_mul_i32 s4, s93, s43
	s_mul_hi_u32 s5, s93, s84
	s_add_i32 s5, s5, s4
	s_mul_i32 s4, s93, s84
	s_add_u32 s4, s4, s2
	s_addc_u32 s5, s5, s89
	v_mov_b64_e32 v[0:1], s[52:53]
	v_cmp_ge_i64_e32 vcc, s[4:5], v[0:1]
	v_cmp_lt_i64_e64 s[6:7], s[4:5], v[0:1]
	s_cbranch_vccnz .LBB0_295
	s_ashr_i32 s5, s4, 31
	s_lshr_b32 s5, s5, 29
	s_add_i32 s5, s4, s5
	s_ashr_i32 s33, s5, 3
	s_and_b32 s5, s5, -8
	s_sub_i32 s4, s4, s5
	s_lshr_b32 s5, s4, 31
	s_add_i32 s5, s86, s5
	s_mul_i32 s4, s5, s4
	s_add_i32 s4, s4, s33
	s_abs_i32 s33, s4
	s_mul_hi_u32 s46, s33, s85
	s_mul_i32 s47, s46, s99
	s_sub_i32 s33, s33, s47
	s_ashr_i32 s5, s4, 31
	s_add_i32 s47, s46, 1
	s_sub_i32 s67, s33, s99
	s_cmp_ge_u32 s33, s99
	s_cselect_b32 s46, s47, s46
	s_cselect_b32 s33, s67, s33
	s_add_i32 s47, s46, 1
	s_cmp_ge_u32 s33, s99
	s_cselect_b32 s33, s47, s46
	s_xor_b32 s33, s33, s5
	s_sub_i32 s5, s33, s5
	s_lshl_b32 s46, s5, 2
	s_sub_i32 s33, s61, s46
	s_min_i32 s47, s33, 4
	s_mul_i32 s5, s5, s99
	s_sub_i32 s4, s4, s5
	s_lshr_b32 s33, s4, 2
	s_and_b32 s4, s4, 3
	s_add_i32 s67, s4, s46
